# phase C pass 1: K-only stages use the idle V halves of the slots, one barrier per two stages
# speedup vs baseline: 1.0125x; 1.0037x over previous
.LBB0_484:
	v_and_b32_e32 v2, 15, v3
	v_bfe_u32 v1, v3, 4, 2
	v_lshlrev_b32_e32 v0, 7, v0
	v_xor_b32_e32 v3, v4, v3
	s_movk_i32 s2, 0x70
	v_and_or_b32 v42, v3, s2, v0
	v_mul_u32_u24_e32 v0, 0x90, v2
	v_lshlrev_b32_e32 v3, 4, v1
	v_add3_u32 v0, v95, v0, v3
	ds_read_b128 v[24:27], v0 offset:32768
	ds_read_b128 v[28:31], v0 offset:32832
	s_cmp_gt_u32 s66, 3
	v_readfirstlane_b32 s67, v107
	v_mov_b32_e32 v32, 0x3f803f80
	s_cselect_b64 s[60:61], -1, 0
	s_cmp_lt_u32 s66, 4
	s_waitcnt vmcnt(11)
	ds_write_b128 v42, v[8:11]
	s_waitcnt vmcnt(10)
	ds_write_b128 v42, v[12:15] offset:8192
	s_waitcnt vmcnt(8)
	ds_write_b128 v42, v[16:19] offset:16384
	ds_write_b128 v42, v[20:23] offset:24576
	s_cbranch_scc1 .LBB0_486
	v_add_co_u32_e32 v4, vcc, 0x4000, v40
	s_nop 1
	v_addc_co_u32_e32 v5, vcc, 0, v41, vcc
	v_add_co_u32_e32 v6, vcc, 0x5000, v40
	s_nop 1
	v_addc_co_u32_e32 v7, vcc, 0, v41, vcc
	global_load_dwordx4 v[8:11], v[4:5], off
	global_load_dwordx4 v[12:15], v[6:7], off
	v_add_co_u32_e32 v4, vcc, 0x6000, v40
	s_nop 1
	v_addc_co_u32_e32 v5, vcc, 0, v41, vcc
	v_add_co_u32_e32 v6, vcc, 0x7000, v40
	s_nop 1
	v_addc_co_u32_e32 v7, vcc, 0, v41, vcc
	global_load_dwordx4 v[16:19], v[4:5], off
	global_load_dwordx4 v[20:23], v[6:7], off

.LBB0_487:
	v_cvt_pk_bf16_f32 v0, v0, v1
	v_cvt_pk_bf16_f32 v1, v2, v3
	v_cvt_pk_bf16_f32 v2, v4, v5
	v_cvt_pk_bf16_f32 v3, v6, v7
	s_waitcnt lgkmcnt(0)
	s_barrier
	s_nop 0
	v_mfma_f32_16x16x32_bf16 v[50:53], v[32:35], v[0:3], v[36:39]
	s_branch .LBB0_488

.LBB0_488:
	s_addk_i32 s66, 0x80
	s_add_i32 s75, s75, 2
	s_add_i32 s77, s77, -1
	s_cmp_le_u32 s77, s73
	s_cbranch_scc0 .LBB0_514
	s_branch .LB3_489
.LBB0_489:
	s_add_i32 s77, s75, -4
	s_cmp_lt_u32 s77, s73
	s_cselect_b64 s[68:69], -1, 0
	s_add_i32 s2, s75, -2
	s_cmp_gt_u32 s2, s73
	s_cbranch_scc1 .Lp1A_w0done
	s_add_i32 s2, s75, -1
	s_cmp_le_u32 s2, s73
	s_cbranch_scc1 .Lp1A_w0relax
	s_waitcnt vmcnt(1)
	ds_write_b128 v42, v[8:11] offset:4096
	s_waitcnt vmcnt(0)
	ds_write_b128 v42, v[12:15] offset:12288
	s_branch .Lp1A_w0done
.Lp1A_w0relax:
	s_waitcnt vmcnt(3)
	ds_write_b128 v42, v[8:11] offset:4096
	s_waitcnt vmcnt(2)
	ds_write_b128 v42, v[12:15] offset:12288
.Lp1A_w0done:
	s_add_i32 s77, s77, 3
	s_cmp_gt_u32 s75, s73
	s_cbranch_scc1 .LBB0_493
	s_mov_b32 s67, s85
	s_sub_i32 s84, s66, 32
	s_lshl_b64 s[2:3], s[66:67], 7
	v_lshl_add_u64 v[0:1], v[40:41], 0, s[2:3]
	s_lshl_b64 s[2:3], s[84:85], 7
	v_lshl_add_u64 v[2:3], v[40:41], 0, s[2:3]
	global_load_dwordx4 v[8:11], v[2:3], off
	global_load_dwordx4 v[12:15], v[0:1], off

.LBB0_501:
	v_cvt_pk_bf16_f32 v0, v0, v1
	v_cvt_pk_bf16_f32 v1, v2, v3
	v_cvt_pk_bf16_f32 v2, v4, v5
	v_cvt_pk_bf16_f32 v3, v6, v7
	s_waitcnt lgkmcnt(0)
	s_andn2_b64 vcc, exec, s[68:69]
	v_mfma_f32_16x16x32_bf16 v[50:53], v[32:35], v[0:3], v[36:39]
	s_cbranch_vccnz .Lp1A_bar
	s_add_i32 s2, s75, -1
	s_cmp_gt_u32 s2, s73
	s_cbranch_scc1 .Lp1A_w1done
	s_cmp_le_u32 s75, s73
	s_cbranch_scc1 .Lp1A_w1relax
	s_waitcnt vmcnt(1)
	ds_write_b128 v42, v[16:19] offset:20480
	s_waitcnt vmcnt(0)
	ds_write_b128 v42, v[20:23] offset:28672
	s_branch .Lp1A_w1done
.Lp1A_w1relax:
	s_waitcnt vmcnt(3)
	ds_write_b128 v42, v[16:19] offset:20480
	s_waitcnt vmcnt(2)
	ds_write_b128 v42, v[20:23] offset:28672
.Lp1A_w1done:
	s_add_i32 s2, s75, 1
	s_cmp_gt_u32 s2, s73
	s_cbranch_scc1 .LBB0_506
	s_add_i32 s2, s66, 32
	s_mov_b32 s3, s85
	s_add_i32 s84, s66, 64
	s_lshl_b64 s[2:3], s[2:3], 7
	s_lshl_b64 s[70:71], s[84:85], 7
	v_lshl_add_u64 v[2:3], v[40:41], 0, s[2:3]
	v_lshl_add_u64 v[0:1], v[40:41], 0, s[70:71]
	global_load_dwordx4 v[16:19], v[2:3], off
	global_load_dwordx4 v[20:23], v[0:1], off

.LB3_489:
	s_add_i32 s77, s75, -4
	s_cmp_lt_u32 s77, s73
	s_cselect_b64 s[68:69], -1, 0
	s_add_i32 s2, s75, -2
	s_cmp_gt_u32 s2, s73
	s_cbranch_scc1 .Lp1B_w0done
	s_add_i32 s2, s75, -1
	s_cmp_le_u32 s2, s73
	s_cbranch_scc1 .Lp1B_w0relax
	s_waitcnt vmcnt(1)
	ds_write_b128 v42, v[8:11]
	s_waitcnt vmcnt(0)
	ds_write_b128 v42, v[12:15] offset:8192
	s_branch .Lp1B_w0done
.Lp1B_w0relax:
	s_waitcnt vmcnt(3)
	ds_write_b128 v42, v[8:11]
	s_waitcnt vmcnt(2)
	ds_write_b128 v42, v[12:15] offset:8192

.LB3_493:
	ds_read_b128 v[0:3], v44 offset:4096
	ds_read_b128 v[4:7], v44 offset:6144
	ds_read_b128 v[36:39], v45 offset:4096
	s_add_i32 s2, s66, 0xfffffeff
	s_cmp_gt_i32 s2, s76
	s_mov_b64 s[70:71], -1
	s_waitcnt lgkmcnt(2)
	v_mfma_f32_16x16x32_bf16 v[0:3], v[0:3], v[24:27], 0
	s_waitcnt lgkmcnt(0)
	v_mfma_f32_16x16x32_bf16 v[0:3], v[36:39], v[28:31], v[0:3]
	ds_read_b128 v[36:39], v45 offset:6144
	v_mfma_f32_16x16x32_bf16 v[4:7], v[4:7], v[24:27], 0
	s_waitcnt lgkmcnt(0)
	v_mfma_f32_16x16x32_bf16 v[4:7], v[36:39], v[28:31], v[4:7]
	s_nop 3
	v_fma_f32 v0, v0, s30, 0
	v_fma_f32 v1, v1, s30, 0
	v_fma_f32 v2, v2, s30, 0
	v_fma_f32 v3, v3, s30, 0
	v_fma_f32 v4, v4, s30, 0
	v_fma_f32 v5, v5, s30, 0
	v_fma_f32 v6, v6, s30, 0
	v_fma_f32 v7, v7, s30, 0
	v_exp_f32_e32 v0, v0
	v_exp_f32_e32 v1, v1
	v_exp_f32_e32 v2, v2
	v_exp_f32_e32 v3, v3
	v_exp_f32_e32 v4, v4
	v_exp_f32_e32 v5, v5
	v_exp_f32_e32 v6, v6
	v_exp_f32_e32 v7, v7
	s_cbranch_scc1 .LB3_495
	s_mov_b64 s[70:71], 0

.LB3_497:
	v_cvt_pk_bf16_f32 v0, v0, v1
	v_cvt_pk_bf16_f32 v1, v2, v3
	v_cvt_pk_bf16_f32 v2, v4, v5
	v_cvt_pk_bf16_f32 v3, v6, v7
	s_add_i32 s2, s66, 0xffffff1f
	s_cmp_gt_i32 s2, s76
	v_mfma_f32_16x16x32_bf16 v[36:39], v[32:35], v[0:3], v[50:53]
	ds_read_b128 v[0:3], v44 offset:12288
	ds_read_b128 v[4:7], v45 offset:12288
	s_nop 0
	ds_read_b128 v[48:51], v44 offset:14336
	ds_read_b128 v[52:55], v45 offset:14336
	s_mov_b64 s[70:71], -1
	s_waitcnt lgkmcnt(3)
	v_mfma_f32_16x16x32_bf16 v[0:3], v[0:3], v[24:27], 0
	s_waitcnt lgkmcnt(2)
	v_mfma_f32_16x16x32_bf16 v[0:3], v[4:7], v[28:31], v[0:3]
	s_waitcnt lgkmcnt(1)
	v_mfma_f32_16x16x32_bf16 v[4:7], v[48:51], v[24:27], 0
	s_waitcnt lgkmcnt(0)
	v_mfma_f32_16x16x32_bf16 v[4:7], v[52:55], v[28:31], v[4:7]
	s_nop 3
	v_fma_f32 v0, v0, s30, 0
	v_fma_f32 v1, v1, s30, 0
	v_fma_f32 v2, v2, s30, 0
	v_fma_f32 v3, v3, s30, 0
	v_exp_f32_e32 v0, v0
	v_fma_f32 v4, v4, s30, 0
	v_fma_f32 v5, v5, s30, 0
	v_fma_f32 v6, v6, s30, 0
	v_fma_f32 v7, v7, s30, 0
	v_exp_f32_e32 v1, v1
	v_exp_f32_e32 v2, v2
	v_exp_f32_e32 v3, v3
	v_exp_f32_e32 v4, v4
	v_exp_f32_e32 v5, v5
	v_exp_f32_e32 v6, v6
	v_exp_f32_e32 v7, v7
	s_cbranch_scc1 .LB3_499
	s_mov_b64 s[70:71], 0

.LB3_501:
	v_cvt_pk_bf16_f32 v0, v0, v1
	v_cvt_pk_bf16_f32 v1, v2, v3
	v_cvt_pk_bf16_f32 v2, v4, v5
	v_cvt_pk_bf16_f32 v3, v6, v7
	s_waitcnt lgkmcnt(0)
	s_andn2_b64 vcc, exec, s[68:69]
	v_mfma_f32_16x16x32_bf16 v[50:53], v[32:35], v[0:3], v[36:39]
	s_cbranch_vccnz .Lp1B_bar
	s_add_i32 s2, s75, -1
	s_cmp_gt_u32 s2, s73
	s_cbranch_scc1 .Lp1B_w1done
	s_cmp_le_u32 s75, s73
	s_cbranch_scc1 .Lp1B_w1relax
	s_waitcnt vmcnt(1)
	ds_write_b128 v42, v[16:19] offset:16384
	s_waitcnt vmcnt(0)
	ds_write_b128 v42, v[20:23] offset:24576
	s_branch .Lp1B_w1done
.Lp1B_w1relax:
	s_waitcnt vmcnt(3)
	ds_write_b128 v42, v[16:19] offset:16384
	s_waitcnt vmcnt(2)
	ds_write_b128 v42, v[20:23] offset:24576

.LB3_506:
	ds_read_b128 v[0:3], v44 offset:20480
	ds_read_b128 v[4:7], v44 offset:22528
	ds_read_b128 v[36:39], v45 offset:20480
	s_add_i32 s2, s66, 0xffffff3f
	s_cmp_gt_i32 s2, s76
	s_mov_b64 s[68:69], -1
	s_waitcnt lgkmcnt(2)
	v_mfma_f32_16x16x32_bf16 v[0:3], v[0:3], v[24:27], 0
	s_waitcnt lgkmcnt(0)
	v_mfma_f32_16x16x32_bf16 v[0:3], v[36:39], v[28:31], v[0:3]
	ds_read_b128 v[36:39], v45 offset:22528
	v_mfma_f32_16x16x32_bf16 v[4:7], v[4:7], v[24:27], 0
	s_waitcnt lgkmcnt(0)
	v_mfma_f32_16x16x32_bf16 v[4:7], v[36:39], v[28:31], v[4:7]
	s_nop 3
	v_fma_f32 v0, v0, s30, 0
	v_fma_f32 v1, v1, s30, 0
	v_fma_f32 v2, v2, s30, 0
	v_fma_f32 v3, v3, s30, 0
	v_fma_f32 v4, v4, s30, 0
	v_fma_f32 v5, v5, s30, 0
	v_fma_f32 v6, v6, s30, 0
	v_fma_f32 v7, v7, s30, 0
	v_exp_f32_e32 v0, v0
	v_exp_f32_e32 v1, v1
	v_exp_f32_e32 v2, v2
	v_exp_f32_e32 v3, v3
	v_exp_f32_e32 v4, v4
	v_exp_f32_e32 v5, v5
	v_exp_f32_e32 v6, v6
	v_exp_f32_e32 v7, v7
	s_cbranch_scc1 .LB3_508
	s_mov_b64 s[68:69], 0

.LB3_510:
	v_cvt_pk_bf16_f32 v0, v0, v1
	v_cvt_pk_bf16_f32 v1, v2, v3
	v_cvt_pk_bf16_f32 v2, v4, v5
	v_cvt_pk_bf16_f32 v3, v6, v7
	s_add_i32 s2, s66, 0xffffff5f
	s_cmp_gt_i32 s2, s76
	v_mfma_f32_16x16x32_bf16 v[36:39], v[32:35], v[0:3], v[50:53]
	ds_read_b128 v[0:3], v44 offset:28672
	ds_read_b128 v[4:7], v45 offset:28672
	s_nop 0
	ds_read_b128 v[48:51], v44 offset:30720
	ds_read_b128 v[52:55], v45 offset:30720
	s_mov_b64 s[68:69], -1
	s_waitcnt lgkmcnt(3)
	v_mfma_f32_16x16x32_bf16 v[0:3], v[0:3], v[24:27], 0
	s_waitcnt lgkmcnt(2)
	v_mfma_f32_16x16x32_bf16 v[0:3], v[4:7], v[28:31], v[0:3]
	s_waitcnt lgkmcnt(1)
	v_mfma_f32_16x16x32_bf16 v[4:7], v[48:51], v[24:27], 0
	s_waitcnt lgkmcnt(0)
	v_mfma_f32_16x16x32_bf16 v[4:7], v[52:55], v[28:31], v[4:7]
	s_nop 3
	v_fma_f32 v0, v0, s30, 0
	v_fma_f32 v1, v1, s30, 0
	v_fma_f32 v2, v2, s30, 0
	v_fma_f32 v3, v3, s30, 0
	v_exp_f32_e32 v0, v0
	v_fma_f32 v4, v4, s30, 0
	v_fma_f32 v5, v5, s30, 0
	v_fma_f32 v6, v6, s30, 0
	v_fma_f32 v7, v7, s30, 0
	v_exp_f32_e32 v1, v1
	v_exp_f32_e32 v2, v2
	v_exp_f32_e32 v3, v3
	v_exp_f32_e32 v4, v4
	v_exp_f32_e32 v5, v5
	v_exp_f32_e32 v6, v6
	v_exp_f32_e32 v7, v7
	s_cbranch_scc1 .LB3_512
	s_mov_b64 s[68:69], 0
